# candidate A plus P5 merge-epilogue MG stores write-through (sc1)
# speedup vs baseline: 1.0095x; 1.0011x over previous
.LBB0_1013:
	s_lshl_b32 s17, s79, 10
	s_or_b32 s22, s17, 0x800
	s_mov_b32 s23, s97
	s_lshl_b64 s[20:21], s[22:23], 2
	v_lshl_add_u32 v70, s82, 8, v224
	s_add_u32 s20, s64, s20
	s_mov_b32 s27, s97
	s_mul_i32 s26, s79, 0x3080000
	s_addc_u32 s21, s65, s21
	v_ashrrev_i32_e32 v71, 31, v70
	v_lshl_add_u64 v[78:79], v[70:71], 2, s[20:21]
	s_lshl_b64 s[20:21], s[26:27], 1
	v_lshl_add_u32 v212, s78, 8, v222
	s_add_u32 s20, s60, s20
	v_mov_b64_e32 v[214:215], s[10:11]
	s_movk_i32 s17, 0x5800
	s_addc_u32 s21, s61, s21
	v_mad_i64_i32 v[72:73], s[24:25], v212, s17, v[214:215]
	s_lshl_b32 s26, s22, 1
	v_lshl_add_u64 v[72:73], v[72:73], 0, s[26:27]
	v_lshlrev_b64 v[210:211], 1, v[70:71]
	v_lshl_add_u64 v[146:147], v[72:73], 0, v[210:211]
	s_movk_i32 s24, 0x3000
	v_add_co_u32_e32 v70, vcc, s24, v146
	v_ashrrev_i32_e32 v213, 31, v212
	s_nop 0
	v_addc_co_u32_e32 v71, vcc, 0, v147, vcc
	global_load_dwordx4 v[226:229], v[70:71], off offset:2048
	global_load_dwordx4 v[82:85], v[78:79], off
	v_lshlrev_b64 v[200:201], 11, v[212:213]
	v_lshl_add_u64 v[70:71], s[20:21], 0, v[200:201]
	v_lshl_add_u64 v[148:149], v[70:71], 0, v[210:211]
	global_load_dwordx4 v[230:233], v[148:149], off
	global_load_dwordx4 v[86:89], v[78:79], off offset:16
	v_or_b32_e32 v70, 16, v212
	v_or_b32_e32 v72, 32, v212
	v_ashrrev_i32_e32 v71, 31, v70
	v_ashrrev_i32_e32 v73, 31, v72
	v_lshlrev_b64 v[220:221], 11, v[70:71]
	v_lshlrev_b64 v[218:219], 11, v[72:73]
	v_or_b32_e32 v80, 48, v212
	v_lshl_add_u64 v[156:157], s[20:21], 0, v[220:221]
	v_lshl_add_u64 v[158:159], s[20:21], 0, v[218:219]
	s_mov_b64 s[28:29], 0x3800
	v_ashrrev_i32_e32 v81, 31, v80
	v_lshl_add_u64 v[156:157], v[156:157], 0, v[210:211]
	v_lshl_add_u64 v[158:159], v[158:159], 0, v[210:211]
	v_lshl_add_u64 v[146:147], v[146:147], 0, s[28:29]
	v_mad_i64_i32 v[150:151], s[22:23], v70, s17, v[214:215]
	v_mad_i64_i32 v[152:153], s[22:23], v72, s17, v[214:215]
	v_mad_i64_i32 v[154:155], s[22:23], v80, s17, v[214:215]
	v_lshlrev_b64 v[216:217], 11, v[80:81]
	global_load_dwordx4 v[70:73], v[78:79], off offset:528
	s_nop 0
	global_load_dwordx4 v[78:81], v[78:79], off offset:512
	v_lshl_add_u64 v[150:151], v[150:151], 0, s[26:27]
	global_load_dwordx4 v[238:241], v[148:149], off offset:256
	global_load_dwordx4 v[186:189], v[156:157], off
	global_load_dwordx4 v[178:181], v[156:157], off offset:256
	global_load_dwordx4 v[170:173], v[158:159], off
	global_load_dwordx4 v[162:165], v[158:159], off offset:256
	global_load_dwordx4 v[242:245], v[146:147], off offset:256
	v_lshl_add_u64 v[150:151], v[150:151], 0, v[210:211]
	v_lshl_add_u64 v[152:153], v[152:153], 0, s[26:27]
	v_lshl_add_u64 v[166:167], v[150:151], 0, s[28:29]
	v_add_co_u32_e32 v150, vcc, s24, v150
	v_lshl_add_u64 v[152:153], v[152:153], 0, v[210:211]
	s_nop 0
	v_addc_co_u32_e32 v151, vcc, 0, v151, vcc
	v_lshl_add_u64 v[154:155], v[154:155], 0, s[26:27]
	v_lshl_add_u64 v[168:169], v[152:153], 0, s[28:29]
	v_add_co_u32_e32 v152, vcc, s24, v152
	v_lshl_add_u64 v[160:161], s[20:21], 0, v[216:217]
	v_lshl_add_u64 v[154:155], v[154:155], 0, v[210:211]
	v_addc_co_u32_e32 v153, vcc, 0, v153, vcc
	v_lshl_add_u64 v[160:161], v[160:161], 0, v[210:211]
	v_add_co_u32_e32 v158, vcc, s24, v154
	v_lshl_add_u64 v[246:247], v[154:155], 0, s[28:29]
	s_nop 0
	v_addc_co_u32_e32 v159, vcc, 0, v155, vcc
	global_load_dwordx4 v[154:157], v[160:161], off
	global_load_dwordx4 v[146:149], v[160:161], off offset:256
	global_load_dwordx4 v[190:193], v[150:151], off offset:2048
	global_load_dwordx4 v[182:185], v[166:167], off offset:256
	global_load_dwordx4 v[174:177], v[152:153], off offset:2048
	s_nop 0
	global_load_dwordx4 v[166:169], v[168:169], off offset:256
	s_waitcnt vmcnt(0)
	v_lshlrev_b32_e32 v150, 16, v226
	v_add_f32_e32 v150, v82, v150
	v_mul_f32_e32 v150, 0xbfb8aa3b, v150
	v_exp_f32_e32 v213, v150
	v_and_b32_e32 v150, 0xffff0000, v226
	v_add_f32_e32 v150, v83, v150
	v_mul_f32_e32 v150, 0xbfb8aa3b, v150
	v_exp_f32_e32 v226, v150
	v_add_f32_e32 v213, 1.0, v213
	v_rcp_f32_e32 v213, v213
	v_lshlrev_b32_e32 v237, 16, v230
	v_add_f32_e32 v226, 1.0, v226
	v_rcp_f32_e32 v226, v226
	v_fmac_f32_e32 v237, v142, v213
	v_and_b32_e32 v142, 0xffff0000, v230
	v_and_b32_e32 v213, 0xffff0000, v227
	v_fmac_f32_e32 v142, v143, v226
	v_lshlrev_b32_e32 v143, 16, v227
	v_add_f32_e32 v143, v84, v143
	v_mul_f32_e32 v143, 0xbfb8aa3b, v143
	v_add_f32_e32 v213, v85, v213
	v_exp_f32_e32 v143, v143
	v_mul_f32_e32 v213, 0xbfb8aa3b, v213
	v_exp_f32_e32 v213, v213
	v_lshlrev_b32_e32 v227, 16, v228
	v_add_f32_e32 v143, 1.0, v143
	v_rcp_f32_e32 v143, v143
	v_add_f32_e32 v213, 1.0, v213
	v_rcp_f32_e32 v213, v213
	v_add_f32_e32 v227, v86, v227
	v_mul_f32_e32 v227, 0xbfb8aa3b, v227
	v_lshlrev_b32_e32 v226, 16, v231
	v_exp_f32_e32 v227, v227
	v_fmac_f32_e32 v226, v144, v143
	v_and_b32_e32 v143, 0xffff0000, v231
	v_fmac_f32_e32 v143, v145, v213
	v_and_b32_e32 v145, 0xffff0000, v228
	v_add_f32_e32 v145, v87, v145
	v_add_f32_e32 v144, 1.0, v227
	v_mul_f32_e32 v145, 0xbfb8aa3b, v145
	v_rcp_f32_e32 v144, v144
	v_exp_f32_e32 v145, v145
	v_lshlrev_b32_e32 v213, 16, v232
	v_and_b32_e32 v227, 0xffff0000, v229
	v_fmac_f32_e32 v213, v138, v144
	v_add_f32_e32 v138, 1.0, v145
	v_lshlrev_b32_e32 v145, 16, v229
	v_add_f32_e32 v145, v88, v145
	v_mul_f32_e32 v145, 0xbfb8aa3b, v145
	v_add_f32_e32 v227, v89, v227
	v_rcp_f32_e32 v138, v138
	v_exp_f32_e32 v145, v145
	v_mul_f32_e32 v227, 0xbfb8aa3b, v227
	v_exp_f32_e32 v227, v227
	v_and_b32_e32 v144, 0xffff0000, v232
	v_fmac_f32_e32 v144, v139, v138
	v_add_f32_e32 v138, 1.0, v145
	v_rcp_f32_e32 v138, v138
	v_add_f32_e32 v139, 1.0, v227
	v_rcp_f32_e32 v139, v139
	v_lshlrev_b32_e32 v145, 16, v233
	v_fmac_f32_e32 v145, v140, v138
	v_and_b32_e32 v227, 0xffff0000, v233
	v_cvt_pk_bf16_f32 v140, v213, v144
	v_lshlrev_b32_e32 v144, 16, v242
	v_fmac_f32_e32 v227, v141, v139
	v_cvt_pk_bf16_f32 v141, v145, v227
	v_add_f32_e32 v144, v78, v144
	v_and_b32_e32 v145, 0xffff0000, v242
	v_mul_f32_e32 v144, 0xbfb8aa3b, v144
	v_add_f32_e32 v145, v79, v145
	v_exp_f32_e32 v144, v144
	v_mul_f32_e32 v145, 0xbfb8aa3b, v145
	v_exp_f32_e32 v145, v145
	v_cvt_pk_bf16_f32 v138, v237, v142
	v_cvt_pk_bf16_f32 v139, v226, v143
	v_lshl_add_u64 v[142:143], s[8:9], 0, v[200:201]
	v_lshl_add_u64 v[142:143], v[142:143], 0, v[210:211]
	global_load_dwordx4 v[158:161], v[158:159], off offset:2048
	s_nop 0
	global_load_dwordx4 v[150:153], v[246:247], off offset:256
	s_nop 0
	global_store_dwordx4 v[142:143], v[138:141], off sc1
	s_nop 1
	v_add_f32_e32 v138, 1.0, v144
	v_rcp_f32_e32 v138, v138
	v_add_f32_e32 v139, 1.0, v145
	v_rcp_f32_e32 v139, v139
	v_lshlrev_b32_e32 v140, 16, v238
	v_fmac_f32_e32 v140, v134, v138
	v_and_b32_e32 v134, 0xffff0000, v238
	v_fmac_f32_e32 v134, v135, v139
	v_lshlrev_b32_e32 v135, 16, v243
	v_add_f32_e32 v135, v80, v135
	v_and_b32_e32 v138, 0xffff0000, v243
	v_mul_f32_e32 v135, 0xbfb8aa3b, v135
	v_add_f32_e32 v138, v81, v138
	v_exp_f32_e32 v135, v135
	v_mul_f32_e32 v138, 0xbfb8aa3b, v138
	v_exp_f32_e32 v138, v138
	v_lshlrev_b32_e32 v141, 16, v244
	v_add_f32_e32 v135, 1.0, v135
	v_rcp_f32_e32 v135, v135
	v_add_f32_e32 v138, 1.0, v138
	v_rcp_f32_e32 v138, v138
	v_add_f32_e32 v141, v70, v141
	v_mul_f32_e32 v141, 0xbfb8aa3b, v141
	v_lshlrev_b32_e32 v139, 16, v239
	v_exp_f32_e32 v141, v141
	v_fmac_f32_e32 v139, v136, v135
	v_and_b32_e32 v135, 0xffff0000, v239
	v_fmac_f32_e32 v135, v137, v138
	v_and_b32_e32 v137, 0xffff0000, v244
	v_add_f32_e32 v137, v71, v137
	v_add_f32_e32 v136, 1.0, v141
	v_mul_f32_e32 v137, 0xbfb8aa3b, v137
	v_rcp_f32_e32 v136, v136
	v_exp_f32_e32 v137, v137
	v_lshlrev_b32_e32 v138, 16, v240
	v_and_b32_e32 v141, 0xffff0000, v245
	v_fmac_f32_e32 v138, v130, v136
	v_add_f32_e32 v130, 1.0, v137
	v_lshlrev_b32_e32 v137, 16, v245
	v_add_f32_e32 v137, v72, v137
	v_mul_f32_e32 v137, 0xbfb8aa3b, v137
	v_add_f32_e32 v141, v73, v141
	v_rcp_f32_e32 v130, v130
	v_exp_f32_e32 v137, v137
	v_mul_f32_e32 v141, 0xbfb8aa3b, v141
	v_exp_f32_e32 v141, v141
	v_and_b32_e32 v136, 0xffff0000, v240
	v_fmac_f32_e32 v136, v131, v130
	v_add_f32_e32 v130, 1.0, v137
	v_rcp_f32_e32 v130, v130
	v_add_f32_e32 v131, 1.0, v141
	v_rcp_f32_e32 v131, v131
	v_lshlrev_b32_e32 v137, 16, v241
	v_fmac_f32_e32 v137, v132, v130
	v_and_b32_e32 v141, 0xffff0000, v241
	v_cvt_pk_bf16_f32 v130, v140, v134
	v_lshlrev_b32_e32 v134, 16, v190
	v_fmac_f32_e32 v141, v133, v131
	v_cvt_pk_bf16_f32 v131, v139, v135
	v_add_f32_e32 v134, v82, v134
	v_and_b32_e32 v135, 0xffff0000, v190
	v_mul_f32_e32 v134, 0xbfb8aa3b, v134
	v_add_f32_e32 v135, v83, v135
	v_exp_f32_e32 v134, v134
	v_mul_f32_e32 v135, 0xbfb8aa3b, v135
	v_exp_f32_e32 v135, v135
	v_cvt_pk_bf16_f32 v132, v138, v136
	v_cvt_pk_bf16_f32 v133, v137, v141
	global_store_dwordx4 v[142:143], v[130:133], off offset:256 sc1
	s_nop 1
	v_add_f32_e32 v130, 1.0, v134
	v_rcp_f32_e32 v130, v130
	v_add_f32_e32 v131, 1.0, v135
	v_rcp_f32_e32 v131, v131
	v_lshlrev_b32_e32 v132, 16, v186
	v_fmac_f32_e32 v132, v126, v130
	v_and_b32_e32 v126, 0xffff0000, v186
	v_fmac_f32_e32 v126, v127, v131
	v_lshlrev_b32_e32 v127, 16, v191
	v_add_f32_e32 v127, v84, v127
	v_and_b32_e32 v130, 0xffff0000, v191
	v_mul_f32_e32 v127, 0xbfb8aa3b, v127
	v_add_f32_e32 v130, v85, v130
	v_exp_f32_e32 v127, v127
	v_mul_f32_e32 v130, 0xbfb8aa3b, v130
	v_exp_f32_e32 v130, v130
	v_lshlrev_b32_e32 v133, 16, v192
	v_add_f32_e32 v127, 1.0, v127
	v_rcp_f32_e32 v127, v127
	v_add_f32_e32 v130, 1.0, v130
	v_rcp_f32_e32 v130, v130
	v_add_f32_e32 v133, v86, v133
	v_mul_f32_e32 v133, 0xbfb8aa3b, v133
	v_lshlrev_b32_e32 v131, 16, v187
	v_exp_f32_e32 v133, v133
	v_fmac_f32_e32 v131, v128, v127
	v_and_b32_e32 v127, 0xffff0000, v187
	v_fmac_f32_e32 v127, v129, v130
	v_and_b32_e32 v129, 0xffff0000, v192
	v_add_f32_e32 v129, v87, v129
	v_add_f32_e32 v128, 1.0, v133
	v_mul_f32_e32 v129, 0xbfb8aa3b, v129
	v_rcp_f32_e32 v128, v128
	v_exp_f32_e32 v129, v129
	v_lshlrev_b32_e32 v130, 16, v188
	v_and_b32_e32 v133, 0xffff0000, v193
	v_fmac_f32_e32 v130, v122, v128
	v_add_f32_e32 v122, 1.0, v129
	v_lshlrev_b32_e32 v129, 16, v193
	v_add_f32_e32 v129, v88, v129
	v_mul_f32_e32 v129, 0xbfb8aa3b, v129
	v_add_f32_e32 v133, v89, v133
	v_rcp_f32_e32 v122, v122
	v_exp_f32_e32 v129, v129
	v_mul_f32_e32 v133, 0xbfb8aa3b, v133
	v_exp_f32_e32 v133, v133
	v_and_b32_e32 v128, 0xffff0000, v188
	v_fmac_f32_e32 v128, v123, v122
	v_add_f32_e32 v122, 1.0, v129
	v_rcp_f32_e32 v122, v122
	v_add_f32_e32 v123, 1.0, v133
	v_rcp_f32_e32 v123, v123
	v_lshlrev_b32_e32 v129, 16, v189
	v_fmac_f32_e32 v129, v124, v122
	v_and_b32_e32 v133, 0xffff0000, v189
	v_cvt_pk_bf16_f32 v124, v130, v128
	v_lshlrev_b32_e32 v128, 16, v182
	v_fmac_f32_e32 v133, v125, v123
	v_cvt_pk_bf16_f32 v125, v129, v133
	v_add_f32_e32 v128, v78, v128
	v_and_b32_e32 v129, 0xffff0000, v182
	v_mul_f32_e32 v128, 0xbfb8aa3b, v128
	v_add_f32_e32 v129, v79, v129
	v_exp_f32_e32 v128, v128
	v_mul_f32_e32 v129, 0xbfb8aa3b, v129
	v_exp_f32_e32 v129, v129
	v_cvt_pk_bf16_f32 v122, v132, v126
	v_cvt_pk_bf16_f32 v123, v131, v127
	v_lshl_add_u64 v[126:127], s[8:9], 0, v[220:221]
	v_lshl_add_u64 v[126:127], v[126:127], 0, v[210:211]
	global_store_dwordx4 v[126:127], v[122:125], off sc1
	s_nop 1
	v_add_f32_e32 v122, 1.0, v128
	v_rcp_f32_e32 v122, v122
	v_add_f32_e32 v123, 1.0, v129
	v_rcp_f32_e32 v123, v123
	v_lshlrev_b32_e32 v124, 16, v178
	v_fmac_f32_e32 v124, v118, v122
	v_and_b32_e32 v118, 0xffff0000, v178
	v_fmac_f32_e32 v118, v119, v123
	v_lshlrev_b32_e32 v119, 16, v183
	v_add_f32_e32 v119, v80, v119
	v_and_b32_e32 v122, 0xffff0000, v183
	v_mul_f32_e32 v119, 0xbfb8aa3b, v119
	v_add_f32_e32 v122, v81, v122
	v_exp_f32_e32 v119, v119
	v_mul_f32_e32 v122, 0xbfb8aa3b, v122
	v_exp_f32_e32 v122, v122
	v_lshlrev_b32_e32 v125, 16, v184
	v_add_f32_e32 v119, 1.0, v119
	v_rcp_f32_e32 v119, v119
	v_add_f32_e32 v122, 1.0, v122
	v_rcp_f32_e32 v122, v122
	v_add_f32_e32 v125, v70, v125
	v_mul_f32_e32 v125, 0xbfb8aa3b, v125
	v_lshlrev_b32_e32 v123, 16, v179
	v_exp_f32_e32 v125, v125
	v_fmac_f32_e32 v123, v120, v119
	v_and_b32_e32 v119, 0xffff0000, v179
	v_fmac_f32_e32 v119, v121, v122
	v_and_b32_e32 v121, 0xffff0000, v184
	v_add_f32_e32 v121, v71, v121
	v_add_f32_e32 v120, 1.0, v125
	v_mul_f32_e32 v121, 0xbfb8aa3b, v121
	v_rcp_f32_e32 v120, v120
	v_exp_f32_e32 v121, v121
	v_lshlrev_b32_e32 v122, 16, v180
	v_and_b32_e32 v125, 0xffff0000, v185
	v_fmac_f32_e32 v122, v114, v120
	v_add_f32_e32 v114, 1.0, v121
	v_lshlrev_b32_e32 v121, 16, v185
	v_add_f32_e32 v121, v72, v121
	v_mul_f32_e32 v121, 0xbfb8aa3b, v121
	v_add_f32_e32 v125, v73, v125
	v_rcp_f32_e32 v114, v114
	v_exp_f32_e32 v121, v121
	v_mul_f32_e32 v125, 0xbfb8aa3b, v125
	v_exp_f32_e32 v125, v125
	v_and_b32_e32 v120, 0xffff0000, v180
	v_fmac_f32_e32 v120, v115, v114
	v_add_f32_e32 v114, 1.0, v121
	v_rcp_f32_e32 v114, v114
	v_add_f32_e32 v115, 1.0, v125
	v_rcp_f32_e32 v115, v115
	v_lshlrev_b32_e32 v121, 16, v181
	v_fmac_f32_e32 v121, v116, v114
	v_and_b32_e32 v125, 0xffff0000, v181
	v_cvt_pk_bf16_f32 v114, v124, v118
	v_lshlrev_b32_e32 v118, 16, v174
	v_fmac_f32_e32 v125, v117, v115
	v_cvt_pk_bf16_f32 v115, v123, v119
	v_add_f32_e32 v118, v82, v118
	v_and_b32_e32 v119, 0xffff0000, v174
	v_mul_f32_e32 v118, 0xbfb8aa3b, v118
	v_add_f32_e32 v119, v83, v119
	v_exp_f32_e32 v118, v118
	v_mul_f32_e32 v119, 0xbfb8aa3b, v119
	v_exp_f32_e32 v119, v119
	v_cvt_pk_bf16_f32 v116, v122, v120
	v_cvt_pk_bf16_f32 v117, v121, v125
	global_store_dwordx4 v[126:127], v[114:117], off offset:256 sc1
	s_nop 1
	v_add_f32_e32 v114, 1.0, v118
	v_rcp_f32_e32 v114, v114
	v_add_f32_e32 v115, 1.0, v119
	v_rcp_f32_e32 v115, v115
	v_lshlrev_b32_e32 v116, 16, v170
	v_fmac_f32_e32 v116, v110, v114
	v_and_b32_e32 v110, 0xffff0000, v170
	v_fmac_f32_e32 v110, v111, v115
	v_lshlrev_b32_e32 v111, 16, v175
	v_add_f32_e32 v111, v84, v111
	v_and_b32_e32 v114, 0xffff0000, v175
	v_mul_f32_e32 v111, 0xbfb8aa3b, v111
	v_add_f32_e32 v114, v85, v114
	v_exp_f32_e32 v111, v111
	v_mul_f32_e32 v114, 0xbfb8aa3b, v114
	v_exp_f32_e32 v114, v114
	v_lshlrev_b32_e32 v117, 16, v176
	v_add_f32_e32 v111, 1.0, v111
	v_rcp_f32_e32 v111, v111
	v_add_f32_e32 v114, 1.0, v114
	v_rcp_f32_e32 v114, v114
	v_add_f32_e32 v117, v86, v117
	v_mul_f32_e32 v117, 0xbfb8aa3b, v117
	v_lshlrev_b32_e32 v115, 16, v171
	v_exp_f32_e32 v117, v117
	v_fmac_f32_e32 v115, v112, v111
	v_and_b32_e32 v111, 0xffff0000, v171
	v_fmac_f32_e32 v111, v113, v114
	v_and_b32_e32 v113, 0xffff0000, v176
	v_add_f32_e32 v113, v87, v113
	v_add_f32_e32 v112, 1.0, v117
	v_mul_f32_e32 v113, 0xbfb8aa3b, v113
	v_rcp_f32_e32 v112, v112
	v_exp_f32_e32 v113, v113
	v_lshlrev_b32_e32 v114, 16, v172
	v_and_b32_e32 v117, 0xffff0000, v177
	v_fmac_f32_e32 v114, v106, v112
	v_add_f32_e32 v106, 1.0, v113
	v_lshlrev_b32_e32 v113, 16, v177
	v_add_f32_e32 v113, v88, v113
	v_mul_f32_e32 v113, 0xbfb8aa3b, v113
	v_add_f32_e32 v117, v89, v117
	v_rcp_f32_e32 v106, v106
	v_exp_f32_e32 v113, v113
	v_mul_f32_e32 v117, 0xbfb8aa3b, v117
	v_exp_f32_e32 v117, v117
	v_and_b32_e32 v112, 0xffff0000, v172
	v_fmac_f32_e32 v112, v107, v106
	v_add_f32_e32 v106, 1.0, v113
	v_rcp_f32_e32 v106, v106
	v_add_f32_e32 v107, 1.0, v117
	v_rcp_f32_e32 v107, v107
	v_lshlrev_b32_e32 v113, 16, v173
	v_fmac_f32_e32 v113, v108, v106
	v_and_b32_e32 v117, 0xffff0000, v173
	v_cvt_pk_bf16_f32 v108, v114, v112
	v_lshlrev_b32_e32 v112, 16, v166
	v_fmac_f32_e32 v117, v109, v107
	v_cvt_pk_bf16_f32 v109, v113, v117
	v_add_f32_e32 v112, v78, v112
	v_and_b32_e32 v113, 0xffff0000, v166
	v_mul_f32_e32 v112, 0xbfb8aa3b, v112
	v_add_f32_e32 v113, v79, v113
	v_exp_f32_e32 v112, v112
	v_mul_f32_e32 v113, 0xbfb8aa3b, v113
	v_exp_f32_e32 v113, v113
	v_cvt_pk_bf16_f32 v106, v116, v110
	v_cvt_pk_bf16_f32 v107, v115, v111
	v_lshl_add_u64 v[110:111], s[8:9], 0, v[218:219]
	v_lshl_add_u64 v[110:111], v[110:111], 0, v[210:211]
	global_store_dwordx4 v[110:111], v[106:109], off sc1
	s_nop 1
	v_add_f32_e32 v106, 1.0, v112
	v_rcp_f32_e32 v106, v106
	v_add_f32_e32 v107, 1.0, v113
	v_rcp_f32_e32 v107, v107
	v_lshlrev_b32_e32 v108, 16, v162
	v_fmac_f32_e32 v108, v102, v106
	v_and_b32_e32 v102, 0xffff0000, v162
	v_fmac_f32_e32 v102, v103, v107
	v_lshlrev_b32_e32 v103, 16, v167
	v_add_f32_e32 v103, v80, v103
	v_and_b32_e32 v106, 0xffff0000, v167
	v_mul_f32_e32 v103, 0xbfb8aa3b, v103
	v_add_f32_e32 v106, v81, v106
	v_exp_f32_e32 v103, v103
	v_mul_f32_e32 v106, 0xbfb8aa3b, v106
	v_exp_f32_e32 v106, v106
	v_lshlrev_b32_e32 v109, 16, v168
	v_add_f32_e32 v103, 1.0, v103
	v_rcp_f32_e32 v103, v103
	v_add_f32_e32 v106, 1.0, v106
	v_rcp_f32_e32 v106, v106
	v_add_f32_e32 v109, v70, v109
	v_mul_f32_e32 v109, 0xbfb8aa3b, v109
	v_lshlrev_b32_e32 v107, 16, v163
	v_exp_f32_e32 v109, v109
	v_fmac_f32_e32 v107, v104, v103
	v_and_b32_e32 v103, 0xffff0000, v163
	v_fmac_f32_e32 v103, v105, v106
	v_and_b32_e32 v105, 0xffff0000, v168
	v_add_f32_e32 v105, v71, v105
	v_add_f32_e32 v104, 1.0, v109
	v_mul_f32_e32 v105, 0xbfb8aa3b, v105
	v_rcp_f32_e32 v104, v104
	v_exp_f32_e32 v105, v105
	v_lshlrev_b32_e32 v106, 16, v164
	v_and_b32_e32 v109, 0xffff0000, v169
	v_fmac_f32_e32 v106, v98, v104
	v_add_f32_e32 v98, 1.0, v105
	v_lshlrev_b32_e32 v105, 16, v169
	v_add_f32_e32 v105, v72, v105
	v_mul_f32_e32 v105, 0xbfb8aa3b, v105
	v_add_f32_e32 v109, v73, v109
	v_rcp_f32_e32 v98, v98
	v_exp_f32_e32 v105, v105
	v_mul_f32_e32 v109, 0xbfb8aa3b, v109
	v_exp_f32_e32 v109, v109
	v_and_b32_e32 v104, 0xffff0000, v164
	v_fmac_f32_e32 v104, v99, v98
	v_add_f32_e32 v98, 1.0, v105
	v_rcp_f32_e32 v98, v98
	v_add_f32_e32 v99, 1.0, v109
	v_rcp_f32_e32 v99, v99
	v_lshlrev_b32_e32 v105, 16, v165
	v_fmac_f32_e32 v105, v100, v98
	v_and_b32_e32 v109, 0xffff0000, v165
	v_cvt_pk_bf16_f32 v98, v108, v102
	s_waitcnt vmcnt(6)
	v_lshlrev_b32_e32 v102, 16, v158
	v_fmac_f32_e32 v109, v101, v99
	v_cvt_pk_bf16_f32 v99, v107, v103
	v_add_f32_e32 v102, v82, v102
	v_and_b32_e32 v103, 0xffff0000, v158
	v_mul_f32_e32 v102, 0xbfb8aa3b, v102
	v_add_f32_e32 v103, v83, v103
	v_exp_f32_e32 v102, v102
	v_mul_f32_e32 v103, 0xbfb8aa3b, v103
	v_exp_f32_e32 v103, v103
	v_cvt_pk_bf16_f32 v100, v106, v104
	v_cvt_pk_bf16_f32 v101, v105, v109
	global_store_dwordx4 v[110:111], v[98:101], off offset:256 sc1
	s_nop 1
	v_add_f32_e32 v98, 1.0, v102
	v_rcp_f32_e32 v98, v98
	v_add_f32_e32 v99, 1.0, v103
	v_rcp_f32_e32 v99, v99
	v_lshlrev_b32_e32 v100, 16, v154
	v_fmac_f32_e32 v100, v94, v98
	v_and_b32_e32 v94, 0xffff0000, v154
	v_fmac_f32_e32 v94, v95, v99
	v_lshlrev_b32_e32 v95, 16, v159
	v_add_f32_e32 v95, v84, v95
	v_and_b32_e32 v98, 0xffff0000, v159
	v_mul_f32_e32 v95, 0xbfb8aa3b, v95
	v_add_f32_e32 v98, v85, v98
	v_exp_f32_e32 v95, v95
	v_mul_f32_e32 v98, 0xbfb8aa3b, v98
	v_exp_f32_e32 v98, v98
	v_lshlrev_b32_e32 v101, 16, v160
	v_add_f32_e32 v95, 1.0, v95
	v_rcp_f32_e32 v95, v95
	v_add_f32_e32 v98, 1.0, v98
	v_rcp_f32_e32 v98, v98
	v_add_f32_e32 v101, v86, v101
	v_mul_f32_e32 v101, 0xbfb8aa3b, v101
	v_lshlrev_b32_e32 v99, 16, v155
	v_exp_f32_e32 v101, v101
	v_fmac_f32_e32 v99, v96, v95
	v_and_b32_e32 v95, 0xffff0000, v155
	v_fmac_f32_e32 v95, v97, v98
	v_and_b32_e32 v97, 0xffff0000, v160
	v_add_f32_e32 v97, v87, v97
	v_add_f32_e32 v96, 1.0, v101
	v_mul_f32_e32 v97, 0xbfb8aa3b, v97
	v_rcp_f32_e32 v96, v96
	v_exp_f32_e32 v97, v97
	v_lshlrev_b32_e32 v98, 16, v156
	v_and_b32_e32 v101, 0xffff0000, v161
	v_fmac_f32_e32 v98, v90, v96
	v_add_f32_e32 v90, 1.0, v97
	v_lshlrev_b32_e32 v97, 16, v161
	v_add_f32_e32 v97, v88, v97
	v_mul_f32_e32 v97, 0xbfb8aa3b, v97
	v_add_f32_e32 v101, v89, v101
	v_rcp_f32_e32 v90, v90
	v_exp_f32_e32 v97, v97
	v_mul_f32_e32 v101, 0xbfb8aa3b, v101
	v_exp_f32_e32 v101, v101
	v_and_b32_e32 v96, 0xffff0000, v156
	v_fmac_f32_e32 v96, v91, v90
	v_add_f32_e32 v90, 1.0, v97
	v_rcp_f32_e32 v90, v90
	v_add_f32_e32 v91, 1.0, v101
	v_rcp_f32_e32 v91, v91
	v_lshlrev_b32_e32 v97, 16, v157
	v_fmac_f32_e32 v97, v92, v90
	v_and_b32_e32 v101, 0xffff0000, v157
	v_cvt_pk_bf16_f32 v92, v98, v96
	s_waitcnt vmcnt(6)
	v_lshlrev_b32_e32 v96, 16, v150
	v_fmac_f32_e32 v101, v93, v91
	v_cvt_pk_bf16_f32 v93, v97, v101
	v_add_f32_e32 v96, v78, v96
	v_and_b32_e32 v97, 0xffff0000, v150
	v_mul_f32_e32 v96, 0xbfb8aa3b, v96
	v_add_f32_e32 v97, v79, v97
	v_exp_f32_e32 v96, v96
	v_mul_f32_e32 v97, 0xbfb8aa3b, v97
	v_exp_f32_e32 v97, v97
	v_cvt_pk_bf16_f32 v90, v100, v94
	v_cvt_pk_bf16_f32 v91, v99, v95
	v_lshl_add_u64 v[94:95], s[8:9], 0, v[216:217]
	v_lshl_add_u64 v[94:95], v[94:95], 0, v[210:211]
	global_store_dwordx4 v[94:95], v[90:93], off sc1
	s_nop 1
	v_add_f32_e32 v90, 1.0, v96
	v_rcp_f32_e32 v90, v90
	v_add_f32_e32 v91, 1.0, v97
	v_rcp_f32_e32 v91, v91
	v_lshlrev_b32_e32 v92, 16, v146
	v_fmac_f32_e32 v92, v74, v90
	v_and_b32_e32 v90, 0xffff0000, v146
	v_fmac_f32_e32 v90, v75, v91
	v_and_b32_e32 v75, 0xffff0000, v151
	v_add_f32_e32 v75, v81, v75
	v_lshlrev_b32_e32 v74, 16, v151
	v_mul_f32_e32 v75, 0xbfb8aa3b, v75
	v_add_f32_e32 v74, v80, v74
	v_exp_f32_e32 v75, v75
	v_mul_f32_e32 v74, 0xbfb8aa3b, v74
	v_exp_f32_e32 v74, v74
	v_lshlrev_b32_e32 v93, 16, v152
	v_add_f32_e32 v75, 1.0, v75
	v_rcp_f32_e32 v75, v75
	v_add_f32_e32 v93, v70, v93
	v_add_f32_e32 v74, 1.0, v74
	v_mul_f32_e32 v93, 0xbfb8aa3b, v93
	v_rcp_f32_e32 v74, v74
	v_exp_f32_e32 v93, v93
	v_and_b32_e32 v96, 0xffff0000, v147
	v_fmac_f32_e32 v96, v77, v75
	v_and_b32_e32 v75, 0xffff0000, v152
	v_lshlrev_b32_e32 v91, 16, v147
	v_add_f32_e32 v75, v71, v75
	v_fmac_f32_e32 v91, v76, v74
	v_add_f32_e32 v74, 1.0, v93
	v_mul_f32_e32 v75, 0xbfb8aa3b, v75
	v_rcp_f32_e32 v74, v74
	v_exp_f32_e32 v75, v75
	v_lshlrev_b32_e32 v93, 16, v148
	v_and_b32_e32 v97, 0xffff0000, v148
	v_fmac_f32_e32 v93, v66, v74
	v_add_f32_e32 v66, 1.0, v75
	v_rcp_f32_e32 v98, v66
	v_lshlrev_b32_e32 v66, 16, v153
	v_add_f32_e32 v66, v72, v66
	v_mul_f32_e32 v99, 0xbfb8aa3b, v66
	v_add_u32_e32 v66, 0x80, v212
	v_mad_i64_i32 v[74:75], s[22:23], v66, s17, v[214:215]
	v_lshl_add_u64 v[74:75], v[74:75], 0, s[26:27]
	v_lshl_add_u64 v[74:75], v[74:75], 0, v[210:211]
	v_add_co_u32_e32 v76, vcc, s24, v74
	v_fmac_f32_e32 v97, v67, v98
	s_nop 0
	v_addc_co_u32_e32 v77, vcc, 0, v75, vcc
	global_load_dwordx4 v[144:147], v[76:77], off offset:2048
	v_exp_f32_e32 v76, v99
	v_and_b32_e32 v77, 0xffff0000, v153
	v_add_f32_e32 v77, v73, v77
	v_mul_f32_e32 v77, 0xbfb8aa3b, v77
	v_exp_f32_e32 v77, v77
	v_add_f32_e32 v67, 1.0, v76
	v_rcp_f32_e32 v98, v67
	v_ashrrev_i32_e32 v67, 31, v66
	v_lshlrev_b64 v[154:155], 11, v[66:67]
	v_lshl_add_u64 v[66:67], s[20:21], 0, v[154:155]
	v_add_f32_e32 v99, 1.0, v77
	v_lshl_add_u64 v[76:77], v[66:67], 0, v[210:211]
	global_load_dwordx4 v[150:153], v[76:77], off
	v_rcp_f32_e32 v66, v99
	v_lshlrev_b32_e32 v99, 16, v149
	v_fmac_f32_e32 v99, v68, v98
	v_and_b32_e32 v98, 0xffff0000, v149
	v_fmac_f32_e32 v98, v69, v66
	v_cvt_pk_bf16_f32 v66, v92, v90
	v_cvt_pk_bf16_f32 v67, v91, v96
	v_cvt_pk_bf16_f32 v68, v93, v97
	v_cvt_pk_bf16_f32 v69, v99, v98
	global_store_dwordx4 v[94:95], v[66:69], off offset:256 sc1
	s_waitcnt vmcnt(2)
	v_lshlrev_b32_e32 v94, 16, v144
	v_lshl_add_u64 v[66:67], v[74:75], 0, s[28:29]
	global_load_dwordx4 v[130:133], v[76:77], off offset:256
	global_load_dwordx4 v[134:137], v[66:67], off offset:256
	v_add_f32_e32 v94, v82, v94
	v_mul_f32_e32 v94, 0xbfb8aa3b, v94
	v_exp_f32_e32 v148, v94
	v_and_b32_e32 v94, 0xffff0000, v144
	v_add_f32_e32 v94, v83, v94
	v_mul_f32_e32 v94, 0xbfb8aa3b, v94
	v_exp_f32_e32 v144, v94
	v_add_u32_e32 v66, 0x90, v212
	v_ashrrev_i32_e32 v67, 31, v66
	v_lshlrev_b64 v[142:143], 11, v[66:67]
	v_mad_i64_i32 v[66:67], s[22:23], v66, s17, v[214:215]
	v_add_f32_e32 v148, 1.0, v148
	v_lshl_add_u64 v[66:67], v[66:67], 0, s[26:27]
	v_rcp_f32_e32 v148, v148
	v_add_f32_e32 v144, 1.0, v144
	v_lshl_add_u64 v[68:69], s[20:21], 0, v[142:143]
	v_lshl_add_u64 v[66:67], v[66:67], 0, v[210:211]
	v_rcp_f32_e32 v144, v144
	v_lshl_add_u64 v[68:69], v[68:69], 0, v[210:211]
	v_lshl_add_u64 v[74:75], v[66:67], 0, s[28:29]
	v_add_co_u32_e32 v66, vcc, s24, v66
	s_waitcnt vmcnt(3)
	v_lshlrev_b32_e32 v149, 16, v150
	v_addc_co_u32_e32 v67, vcc, 0, v67, vcc
	global_load_dwordx4 v[122:125], v[68:69], off
	global_load_dwordx4 v[114:117], v[68:69], off offset:256
	global_load_dwordx4 v[126:129], v[66:67], off offset:2048
	global_load_dwordx4 v[118:121], v[74:75], off offset:256
	v_fmac_f32_e32 v149, v62, v148
	v_and_b32_e32 v62, 0xffff0000, v150
	v_fmac_f32_e32 v62, v63, v144
	v_lshlrev_b32_e32 v63, 16, v145
	v_add_f32_e32 v63, v84, v63
	v_and_b32_e32 v144, 0xffff0000, v145
	v_mul_f32_e32 v63, 0xbfb8aa3b, v63
	v_add_f32_e32 v144, v85, v144
	v_exp_f32_e32 v63, v63
	v_mul_f32_e32 v144, 0xbfb8aa3b, v144
	v_exp_f32_e32 v144, v144
	v_lshlrev_b32_e32 v148, 16, v146
	v_add_f32_e32 v63, 1.0, v63
	v_rcp_f32_e32 v63, v63
	v_add_f32_e32 v144, 1.0, v144
	v_rcp_f32_e32 v144, v144
	v_add_f32_e32 v148, v86, v148
	v_mul_f32_e32 v148, 0xbfb8aa3b, v148
	v_lshlrev_b32_e32 v145, 16, v151
	v_exp_f32_e32 v148, v148
	v_fmac_f32_e32 v145, v64, v63
	v_and_b32_e32 v63, 0xffff0000, v151
	v_fmac_f32_e32 v63, v65, v144
	v_and_b32_e32 v65, 0xffff0000, v146
	v_add_f32_e32 v65, v87, v65
	v_add_f32_e32 v64, 1.0, v148
	v_mul_f32_e32 v65, 0xbfb8aa3b, v65
	v_rcp_f32_e32 v64, v64
	v_exp_f32_e32 v65, v65
	v_lshlrev_b32_e32 v144, 16, v152
	v_and_b32_e32 v146, 0xffff0000, v147
	v_fmac_f32_e32 v144, v58, v64
	v_add_f32_e32 v58, 1.0, v65
	v_lshlrev_b32_e32 v65, 16, v147
	v_add_f32_e32 v65, v88, v65
	v_mul_f32_e32 v65, 0xbfb8aa3b, v65
	v_add_f32_e32 v146, v89, v146
	v_rcp_f32_e32 v58, v58
	v_exp_f32_e32 v65, v65
	v_mul_f32_e32 v146, 0xbfb8aa3b, v146
	v_exp_f32_e32 v146, v146
	v_add_u32_e32 v66, 0xa0, v212
	v_ashrrev_i32_e32 v67, 31, v66
	v_and_b32_e32 v64, 0xffff0000, v152
	v_lshlrev_b64 v[140:141], 11, v[66:67]
	v_mad_i64_i32 v[66:67], s[22:23], v66, s17, v[214:215]
	v_fmac_f32_e32 v64, v59, v58
	v_add_f32_e32 v58, 1.0, v65
	v_lshl_add_u64 v[66:67], v[66:67], 0, s[26:27]
	v_rcp_f32_e32 v58, v58
	v_add_f32_e32 v59, 1.0, v146
	v_lshl_add_u64 v[68:69], s[20:21], 0, v[140:141]
	v_lshl_add_u64 v[66:67], v[66:67], 0, v[210:211]
	v_rcp_f32_e32 v59, v59
	v_lshl_add_u64 v[68:69], v[68:69], 0, v[210:211]
	v_lshl_add_u64 v[74:75], v[66:67], 0, s[28:29]
	v_add_co_u32_e32 v66, vcc, s24, v66
	v_lshlrev_b32_e32 v65, 16, v153
	s_nop 0
	v_addc_co_u32_e32 v67, vcc, 0, v67, vcc
	global_load_dwordx4 v[106:109], v[68:69], off
	global_load_dwordx4 v[98:101], v[68:69], off offset:256
	global_load_dwordx4 v[110:113], v[66:67], off offset:2048
	global_load_dwordx4 v[102:105], v[74:75], off offset:256
	v_add_u32_e32 v66, 0xb0, v212
	v_ashrrev_i32_e32 v67, 31, v66
	v_fmac_f32_e32 v65, v60, v58
	v_and_b32_e32 v146, 0xffff0000, v153
	v_cvt_pk_bf16_f32 v60, v144, v64
	s_waitcnt vmcnt(8)
	v_lshlrev_b32_e32 v64, 16, v134
	v_lshlrev_b64 v[138:139], 11, v[66:67]
	v_fmac_f32_e32 v146, v61, v59
	v_cvt_pk_bf16_f32 v61, v65, v146
	v_add_f32_e32 v64, v78, v64
	v_and_b32_e32 v65, 0xffff0000, v134
	v_lshl_add_u64 v[68:69], s[20:21], 0, v[138:139]
	v_mad_i64_i32 v[66:67], s[20:21], v66, s17, v[214:215]
	v_mul_f32_e32 v64, 0xbfb8aa3b, v64
	v_add_f32_e32 v65, v79, v65
	v_lshl_add_u64 v[66:67], v[66:67], 0, s[26:27]
	v_exp_f32_e32 v64, v64
	v_mul_f32_e32 v65, 0xbfb8aa3b, v65
	v_lshl_add_u64 v[66:67], v[66:67], 0, v[210:211]
	v_exp_f32_e32 v65, v65
	v_add_co_u32_e32 v76, vcc, s24, v66
	v_cvt_pk_bf16_f32 v58, v149, v62
	v_cvt_pk_bf16_f32 v59, v145, v63
	v_lshl_add_u64 v[62:63], s[8:9], 0, v[154:155]
	v_lshl_add_u64 v[68:69], v[68:69], 0, v[210:211]
	v_lshl_add_u64 v[74:75], v[66:67], 0, s[28:29]
	v_addc_co_u32_e32 v77, vcc, 0, v67, vcc
	v_lshl_add_u64 v[62:63], v[62:63], 0, v[210:211]
	global_load_dwordx4 v[90:93], v[68:69], off
	s_nop 0
	global_load_dwordx4 v[66:69], v[68:69], off offset:256
	s_nop 0
	global_load_dwordx4 v[94:97], v[76:77], off offset:2048
	s_nop 0
	global_load_dwordx4 v[74:77], v[74:75], off offset:256
	s_and_b64 vcc, exec, s[2:3]
	global_store_dwordx4 v[62:63], v[58:61], off sc1
	s_mov_b64 s[2:3], -1
	s_nop 0
	v_add_f32_e32 v58, 1.0, v64
	v_rcp_f32_e32 v58, v58
	v_add_f32_e32 v59, 1.0, v65
	v_rcp_f32_e32 v59, v59
	v_lshlrev_b32_e32 v60, 16, v130
	v_fmac_f32_e32 v60, v54, v58
	v_and_b32_e32 v54, 0xffff0000, v130
	v_fmac_f32_e32 v54, v55, v59
	v_lshlrev_b32_e32 v55, 16, v135
	v_add_f32_e32 v55, v80, v55
	v_and_b32_e32 v58, 0xffff0000, v135
	v_mul_f32_e32 v55, 0xbfb8aa3b, v55
	v_add_f32_e32 v58, v81, v58
	v_exp_f32_e32 v55, v55
	v_mul_f32_e32 v58, 0xbfb8aa3b, v58
	v_exp_f32_e32 v58, v58
	v_lshlrev_b32_e32 v61, 16, v136
	v_add_f32_e32 v55, 1.0, v55
	v_rcp_f32_e32 v55, v55
	v_add_f32_e32 v58, 1.0, v58
	v_rcp_f32_e32 v58, v58
	v_add_f32_e32 v61, v70, v61
	v_mul_f32_e32 v61, 0xbfb8aa3b, v61
	v_lshlrev_b32_e32 v59, 16, v131
	v_exp_f32_e32 v61, v61
	v_fmac_f32_e32 v59, v56, v55
	v_and_b32_e32 v55, 0xffff0000, v131
	v_fmac_f32_e32 v55, v57, v58
	v_and_b32_e32 v57, 0xffff0000, v136
	v_add_f32_e32 v57, v71, v57
	v_add_f32_e32 v56, 1.0, v61
	v_mul_f32_e32 v57, 0xbfb8aa3b, v57
	v_rcp_f32_e32 v56, v56
	v_exp_f32_e32 v57, v57
	v_lshlrev_b32_e32 v58, 16, v132
	v_and_b32_e32 v61, 0xffff0000, v137
	v_fmac_f32_e32 v58, v50, v56
	v_add_f32_e32 v50, 1.0, v57
	v_lshlrev_b32_e32 v57, 16, v137
	v_add_f32_e32 v57, v72, v57
	v_mul_f32_e32 v57, 0xbfb8aa3b, v57
	v_add_f32_e32 v61, v73, v61
	v_rcp_f32_e32 v50, v50
	v_exp_f32_e32 v57, v57
	v_mul_f32_e32 v61, 0xbfb8aa3b, v61
	v_exp_f32_e32 v61, v61
	v_and_b32_e32 v56, 0xffff0000, v132
	v_fmac_f32_e32 v56, v51, v50
	v_add_f32_e32 v50, 1.0, v57
	v_rcp_f32_e32 v50, v50
	v_add_f32_e32 v51, 1.0, v61
	v_rcp_f32_e32 v51, v51
	v_lshlrev_b32_e32 v57, 16, v133
	v_fmac_f32_e32 v57, v52, v50
	v_and_b32_e32 v61, 0xffff0000, v133
	v_cvt_pk_bf16_f32 v50, v60, v54
	s_waitcnt vmcnt(10)
	v_lshlrev_b32_e32 v54, 16, v126
	v_fmac_f32_e32 v61, v53, v51
	v_cvt_pk_bf16_f32 v51, v59, v55
	v_add_f32_e32 v54, v82, v54
	v_and_b32_e32 v55, 0xffff0000, v126
	v_mul_f32_e32 v54, 0xbfb8aa3b, v54
	v_add_f32_e32 v55, v83, v55
	v_exp_f32_e32 v54, v54
	v_mul_f32_e32 v55, 0xbfb8aa3b, v55
	v_exp_f32_e32 v55, v55
	v_cvt_pk_bf16_f32 v52, v58, v56
	v_cvt_pk_bf16_f32 v53, v57, v61
	global_store_dwordx4 v[62:63], v[50:53], off offset:256 sc1
	s_nop 1
	v_add_f32_e32 v50, 1.0, v54
	v_rcp_f32_e32 v50, v50
	v_add_f32_e32 v51, 1.0, v55
	v_rcp_f32_e32 v51, v51
	v_lshlrev_b32_e32 v52, 16, v122
	v_fmac_f32_e32 v52, v46, v50
	v_and_b32_e32 v46, 0xffff0000, v122
	v_fmac_f32_e32 v46, v47, v51
	v_lshlrev_b32_e32 v47, 16, v127
	v_add_f32_e32 v47, v84, v47
	v_and_b32_e32 v50, 0xffff0000, v127
	v_mul_f32_e32 v47, 0xbfb8aa3b, v47
	v_add_f32_e32 v50, v85, v50
	v_exp_f32_e32 v47, v47
	v_mul_f32_e32 v50, 0xbfb8aa3b, v50
	v_exp_f32_e32 v50, v50
	v_lshlrev_b32_e32 v53, 16, v128
	v_add_f32_e32 v47, 1.0, v47
	v_rcp_f32_e32 v47, v47
	v_add_f32_e32 v50, 1.0, v50
	v_rcp_f32_e32 v50, v50
	v_add_f32_e32 v53, v86, v53
	v_mul_f32_e32 v53, 0xbfb8aa3b, v53
	v_lshlrev_b32_e32 v51, 16, v123
	v_exp_f32_e32 v53, v53
	v_fmac_f32_e32 v51, v48, v47
	v_and_b32_e32 v47, 0xffff0000, v123
	v_fmac_f32_e32 v47, v49, v50
	v_and_b32_e32 v49, 0xffff0000, v128
	v_add_f32_e32 v49, v87, v49
	v_add_f32_e32 v48, 1.0, v53
	v_mul_f32_e32 v49, 0xbfb8aa3b, v49
	v_rcp_f32_e32 v48, v48
	v_exp_f32_e32 v49, v49
	v_lshlrev_b32_e32 v50, 16, v124
	v_and_b32_e32 v53, 0xffff0000, v129
	v_fmac_f32_e32 v50, v42, v48
	v_add_f32_e32 v42, 1.0, v49
	v_lshlrev_b32_e32 v49, 16, v129
	v_add_f32_e32 v49, v88, v49
	v_mul_f32_e32 v49, 0xbfb8aa3b, v49
	v_add_f32_e32 v53, v89, v53
	v_rcp_f32_e32 v42, v42
	v_exp_f32_e32 v49, v49
	v_mul_f32_e32 v53, 0xbfb8aa3b, v53
	v_exp_f32_e32 v53, v53
	v_and_b32_e32 v48, 0xffff0000, v124
	v_fmac_f32_e32 v48, v43, v42
	v_add_f32_e32 v42, 1.0, v49
	v_rcp_f32_e32 v42, v42
	v_add_f32_e32 v43, 1.0, v53
	v_rcp_f32_e32 v43, v43
	v_lshlrev_b32_e32 v49, 16, v125
	v_fmac_f32_e32 v49, v44, v42
	v_and_b32_e32 v53, 0xffff0000, v125
	v_cvt_pk_bf16_f32 v44, v50, v48
	s_waitcnt vmcnt(10)
	v_lshlrev_b32_e32 v48, 16, v118
	v_fmac_f32_e32 v53, v45, v43
	v_cvt_pk_bf16_f32 v45, v49, v53
	v_add_f32_e32 v48, v78, v48
	v_and_b32_e32 v49, 0xffff0000, v118
	v_mul_f32_e32 v48, 0xbfb8aa3b, v48
	v_add_f32_e32 v49, v79, v49
	v_exp_f32_e32 v48, v48
	v_mul_f32_e32 v49, 0xbfb8aa3b, v49
	v_exp_f32_e32 v49, v49
	v_cvt_pk_bf16_f32 v42, v52, v46
	v_cvt_pk_bf16_f32 v43, v51, v47
	v_lshl_add_u64 v[46:47], s[8:9], 0, v[142:143]
	v_lshl_add_u64 v[46:47], v[46:47], 0, v[210:211]
	global_store_dwordx4 v[46:47], v[42:45], off sc1
	s_nop 1
	v_add_f32_e32 v42, 1.0, v48
	v_rcp_f32_e32 v42, v42
	v_add_f32_e32 v43, 1.0, v49
	v_rcp_f32_e32 v43, v43
	v_lshlrev_b32_e32 v44, 16, v114
	v_fmac_f32_e32 v44, v38, v42
	v_and_b32_e32 v38, 0xffff0000, v114
	v_fmac_f32_e32 v38, v39, v43
	v_lshlrev_b32_e32 v39, 16, v119
	v_add_f32_e32 v39, v80, v39
	v_and_b32_e32 v42, 0xffff0000, v119
	v_mul_f32_e32 v39, 0xbfb8aa3b, v39
	v_add_f32_e32 v42, v81, v42
	v_exp_f32_e32 v39, v39
	v_mul_f32_e32 v42, 0xbfb8aa3b, v42
	v_exp_f32_e32 v42, v42
	v_lshlrev_b32_e32 v45, 16, v120
	v_add_f32_e32 v39, 1.0, v39
	v_rcp_f32_e32 v39, v39
	v_add_f32_e32 v42, 1.0, v42
	v_rcp_f32_e32 v42, v42
	v_add_f32_e32 v45, v70, v45
	v_mul_f32_e32 v45, 0xbfb8aa3b, v45
	v_lshlrev_b32_e32 v43, 16, v115
	v_exp_f32_e32 v45, v45
	v_fmac_f32_e32 v43, v40, v39
	v_and_b32_e32 v39, 0xffff0000, v115
	v_fmac_f32_e32 v39, v41, v42
	v_and_b32_e32 v41, 0xffff0000, v120
	v_add_f32_e32 v41, v71, v41
	v_add_f32_e32 v40, 1.0, v45
	v_mul_f32_e32 v41, 0xbfb8aa3b, v41
	v_rcp_f32_e32 v40, v40
	v_exp_f32_e32 v41, v41
	v_lshlrev_b32_e32 v42, 16, v116
	v_and_b32_e32 v45, 0xffff0000, v121
	v_fmac_f32_e32 v42, v34, v40
	v_add_f32_e32 v34, 1.0, v41
	v_lshlrev_b32_e32 v41, 16, v121
	v_add_f32_e32 v41, v72, v41
	v_mul_f32_e32 v41, 0xbfb8aa3b, v41
	v_add_f32_e32 v45, v73, v45
	v_rcp_f32_e32 v34, v34
	v_exp_f32_e32 v41, v41
	v_mul_f32_e32 v45, 0xbfb8aa3b, v45
	v_exp_f32_e32 v45, v45
	v_and_b32_e32 v40, 0xffff0000, v116
	v_fmac_f32_e32 v40, v35, v34
	v_add_f32_e32 v34, 1.0, v41
	v_rcp_f32_e32 v34, v34
	v_add_f32_e32 v35, 1.0, v45
	v_rcp_f32_e32 v35, v35
	v_lshlrev_b32_e32 v41, 16, v117
	v_fmac_f32_e32 v41, v36, v34
	v_and_b32_e32 v45, 0xffff0000, v117
	v_cvt_pk_bf16_f32 v34, v44, v38
	s_waitcnt vmcnt(8)
	v_lshlrev_b32_e32 v38, 16, v110
	v_fmac_f32_e32 v45, v37, v35
	v_cvt_pk_bf16_f32 v35, v43, v39
	v_add_f32_e32 v38, v82, v38
	v_and_b32_e32 v39, 0xffff0000, v110
	v_mul_f32_e32 v38, 0xbfb8aa3b, v38
	v_add_f32_e32 v39, v83, v39
	v_exp_f32_e32 v38, v38
	v_mul_f32_e32 v39, 0xbfb8aa3b, v39
	v_exp_f32_e32 v39, v39
	v_cvt_pk_bf16_f32 v36, v42, v40
	v_cvt_pk_bf16_f32 v37, v41, v45
	global_store_dwordx4 v[46:47], v[34:37], off offset:256 sc1
	s_nop 1
	v_add_f32_e32 v34, 1.0, v38
	v_rcp_f32_e32 v34, v34
	v_add_f32_e32 v35, 1.0, v39
	v_rcp_f32_e32 v35, v35
	v_lshlrev_b32_e32 v36, 16, v106
	v_fmac_f32_e32 v36, v30, v34
	v_and_b32_e32 v30, 0xffff0000, v106
	v_fmac_f32_e32 v30, v31, v35
	v_lshlrev_b32_e32 v31, 16, v111
	v_add_f32_e32 v31, v84, v31
	v_and_b32_e32 v34, 0xffff0000, v111
	v_mul_f32_e32 v31, 0xbfb8aa3b, v31
	v_add_f32_e32 v34, v85, v34
	v_exp_f32_e32 v31, v31
	v_mul_f32_e32 v34, 0xbfb8aa3b, v34
	v_exp_f32_e32 v34, v34
	v_lshlrev_b32_e32 v37, 16, v112
	v_add_f32_e32 v31, 1.0, v31
	v_rcp_f32_e32 v31, v31
	v_add_f32_e32 v34, 1.0, v34
	v_rcp_f32_e32 v34, v34
	v_add_f32_e32 v37, v86, v37
	v_mul_f32_e32 v37, 0xbfb8aa3b, v37
	v_lshlrev_b32_e32 v35, 16, v107
	v_exp_f32_e32 v37, v37
	v_fmac_f32_e32 v35, v32, v31
	v_and_b32_e32 v31, 0xffff0000, v107
	v_fmac_f32_e32 v31, v33, v34
	v_and_b32_e32 v33, 0xffff0000, v112
	v_add_f32_e32 v33, v87, v33
	v_add_f32_e32 v32, 1.0, v37
	v_mul_f32_e32 v33, 0xbfb8aa3b, v33
	v_rcp_f32_e32 v32, v32
	v_exp_f32_e32 v33, v33
	v_lshlrev_b32_e32 v34, 16, v108
	v_and_b32_e32 v37, 0xffff0000, v113
	v_fmac_f32_e32 v34, v26, v32
	v_add_f32_e32 v26, 1.0, v33
	v_lshlrev_b32_e32 v33, 16, v113
	v_add_f32_e32 v33, v88, v33
	v_mul_f32_e32 v33, 0xbfb8aa3b, v33
	v_add_f32_e32 v37, v89, v37
	v_rcp_f32_e32 v26, v26
	v_exp_f32_e32 v33, v33
	v_mul_f32_e32 v37, 0xbfb8aa3b, v37
	v_exp_f32_e32 v37, v37
	v_and_b32_e32 v32, 0xffff0000, v108
	v_fmac_f32_e32 v32, v27, v26
	v_add_f32_e32 v26, 1.0, v33
	v_rcp_f32_e32 v26, v26
	v_add_f32_e32 v27, 1.0, v37
	v_rcp_f32_e32 v27, v27
	v_lshlrev_b32_e32 v33, 16, v109
	v_fmac_f32_e32 v33, v28, v26
	v_and_b32_e32 v37, 0xffff0000, v109
	v_cvt_pk_bf16_f32 v28, v34, v32
	s_waitcnt vmcnt(8)
	v_lshlrev_b32_e32 v32, 16, v102
	v_fmac_f32_e32 v37, v29, v27
	v_cvt_pk_bf16_f32 v29, v33, v37
	v_add_f32_e32 v32, v78, v32
	v_and_b32_e32 v33, 0xffff0000, v102
	v_mul_f32_e32 v32, 0xbfb8aa3b, v32
	v_add_f32_e32 v33, v79, v33
	v_exp_f32_e32 v32, v32
	v_mul_f32_e32 v33, 0xbfb8aa3b, v33
	v_exp_f32_e32 v33, v33
	v_cvt_pk_bf16_f32 v26, v36, v30
	v_cvt_pk_bf16_f32 v27, v35, v31
	v_lshl_add_u64 v[30:31], s[8:9], 0, v[140:141]
	v_lshl_add_u64 v[30:31], v[30:31], 0, v[210:211]
	global_store_dwordx4 v[30:31], v[26:29], off sc1
	s_nop 1
	v_add_f32_e32 v26, 1.0, v32
	v_rcp_f32_e32 v26, v26
	v_add_f32_e32 v27, 1.0, v33
	v_rcp_f32_e32 v27, v27
	v_lshlrev_b32_e32 v28, 16, v98
	v_fmac_f32_e32 v28, v22, v26
	v_and_b32_e32 v22, 0xffff0000, v98
	v_fmac_f32_e32 v22, v23, v27
	v_lshlrev_b32_e32 v23, 16, v103
	v_add_f32_e32 v23, v80, v23
	v_and_b32_e32 v26, 0xffff0000, v103
	v_mul_f32_e32 v23, 0xbfb8aa3b, v23
	v_add_f32_e32 v26, v81, v26
	v_exp_f32_e32 v23, v23
	v_mul_f32_e32 v26, 0xbfb8aa3b, v26
	v_exp_f32_e32 v26, v26
	v_lshlrev_b32_e32 v29, 16, v104
	v_add_f32_e32 v23, 1.0, v23
	v_rcp_f32_e32 v23, v23
	v_add_f32_e32 v26, 1.0, v26
	v_rcp_f32_e32 v26, v26
	v_add_f32_e32 v29, v70, v29
	v_mul_f32_e32 v29, 0xbfb8aa3b, v29
	v_lshlrev_b32_e32 v27, 16, v99
	v_exp_f32_e32 v29, v29
	v_fmac_f32_e32 v27, v24, v23
	v_and_b32_e32 v23, 0xffff0000, v99
	v_fmac_f32_e32 v23, v25, v26
	v_and_b32_e32 v25, 0xffff0000, v104
	v_add_f32_e32 v25, v71, v25
	v_add_f32_e32 v24, 1.0, v29
	v_mul_f32_e32 v25, 0xbfb8aa3b, v25
	v_rcp_f32_e32 v24, v24
	v_exp_f32_e32 v25, v25
	v_lshlrev_b32_e32 v26, 16, v100
	v_and_b32_e32 v29, 0xffff0000, v105
	v_fmac_f32_e32 v26, v18, v24
	v_add_f32_e32 v18, 1.0, v25
	v_lshlrev_b32_e32 v25, 16, v105
	v_add_f32_e32 v25, v72, v25
	v_mul_f32_e32 v25, 0xbfb8aa3b, v25
	v_add_f32_e32 v29, v73, v29
	v_rcp_f32_e32 v18, v18
	v_exp_f32_e32 v25, v25
	v_mul_f32_e32 v29, 0xbfb8aa3b, v29
	v_exp_f32_e32 v29, v29
	v_and_b32_e32 v24, 0xffff0000, v100
	v_fmac_f32_e32 v24, v19, v18
	v_add_f32_e32 v18, 1.0, v25
	v_rcp_f32_e32 v18, v18
	v_add_f32_e32 v19, 1.0, v29
	v_rcp_f32_e32 v19, v19
	v_lshlrev_b32_e32 v25, 16, v101
	v_fmac_f32_e32 v25, v20, v18
	v_and_b32_e32 v29, 0xffff0000, v101
	v_cvt_pk_bf16_f32 v18, v28, v22
	s_waitcnt vmcnt(6)
	v_lshlrev_b32_e32 v22, 16, v94
	v_fmac_f32_e32 v29, v21, v19
	v_cvt_pk_bf16_f32 v19, v27, v23
	v_add_f32_e32 v22, v82, v22
	v_and_b32_e32 v23, 0xffff0000, v94
	v_mul_f32_e32 v22, 0xbfb8aa3b, v22
	v_add_f32_e32 v23, v83, v23
	v_exp_f32_e32 v22, v22
	v_mul_f32_e32 v23, 0xbfb8aa3b, v23
	v_exp_f32_e32 v23, v23
	v_cvt_pk_bf16_f32 v20, v26, v24
	v_cvt_pk_bf16_f32 v21, v25, v29
	global_store_dwordx4 v[30:31], v[18:21], off offset:256 sc1
	s_nop 1
	v_add_f32_e32 v18, 1.0, v22
	v_rcp_f32_e32 v18, v18
	v_add_f32_e32 v19, 1.0, v23
	v_rcp_f32_e32 v19, v19
	v_lshlrev_b32_e32 v20, 16, v90
	v_fmac_f32_e32 v20, v14, v18
	v_and_b32_e32 v14, 0xffff0000, v90
	v_fmac_f32_e32 v14, v15, v19
	v_lshlrev_b32_e32 v15, 16, v95
	v_add_f32_e32 v15, v84, v15
	v_and_b32_e32 v18, 0xffff0000, v95
	v_mul_f32_e32 v15, 0xbfb8aa3b, v15
	v_add_f32_e32 v18, v85, v18
	v_exp_f32_e32 v15, v15
	v_mul_f32_e32 v18, 0xbfb8aa3b, v18
	v_exp_f32_e32 v18, v18
	v_lshlrev_b32_e32 v21, 16, v96
	v_add_f32_e32 v15, 1.0, v15
	v_rcp_f32_e32 v15, v15
	v_add_f32_e32 v18, 1.0, v18
	v_rcp_f32_e32 v18, v18
	v_add_f32_e32 v21, v86, v21
	v_mul_f32_e32 v21, 0xbfb8aa3b, v21
	v_lshlrev_b32_e32 v19, 16, v91
	v_exp_f32_e32 v21, v21
	v_fmac_f32_e32 v19, v16, v15
	v_and_b32_e32 v15, 0xffff0000, v91
	v_fmac_f32_e32 v15, v17, v18
	v_and_b32_e32 v17, 0xffff0000, v96
	v_add_f32_e32 v17, v87, v17
	v_add_f32_e32 v16, 1.0, v21
	v_mul_f32_e32 v17, 0xbfb8aa3b, v17
	v_rcp_f32_e32 v16, v16
	v_exp_f32_e32 v17, v17
	v_lshlrev_b32_e32 v18, 16, v92
	v_and_b32_e32 v21, 0xffff0000, v97
	v_fmac_f32_e32 v18, v10, v16
	v_add_f32_e32 v10, 1.0, v17
	v_lshlrev_b32_e32 v17, 16, v97
	v_add_f32_e32 v17, v88, v17
	v_mul_f32_e32 v17, 0xbfb8aa3b, v17
	v_add_f32_e32 v21, v89, v21
	v_rcp_f32_e32 v10, v10
	v_exp_f32_e32 v17, v17
	v_mul_f32_e32 v21, 0xbfb8aa3b, v21
	v_exp_f32_e32 v21, v21
	v_and_b32_e32 v16, 0xffff0000, v92
	v_fmac_f32_e32 v16, v11, v10
	v_add_f32_e32 v10, 1.0, v17
	v_rcp_f32_e32 v10, v10
	v_add_f32_e32 v11, 1.0, v21
	v_rcp_f32_e32 v11, v11
	v_lshlrev_b32_e32 v17, 16, v93
	v_fmac_f32_e32 v17, v12, v10
	v_and_b32_e32 v21, 0xffff0000, v93
	v_cvt_pk_bf16_f32 v12, v18, v16
	s_waitcnt vmcnt(6)
	v_lshlrev_b32_e32 v16, 16, v74
	v_fmac_f32_e32 v21, v13, v11
	v_cvt_pk_bf16_f32 v13, v17, v21
	v_add_f32_e32 v16, v78, v16
	v_and_b32_e32 v17, 0xffff0000, v74
	v_mul_f32_e32 v16, 0xbfb8aa3b, v16
	v_add_f32_e32 v17, v79, v17
	v_exp_f32_e32 v16, v16
	v_mul_f32_e32 v17, 0xbfb8aa3b, v17
	v_exp_f32_e32 v17, v17
	v_cvt_pk_bf16_f32 v10, v20, v14
	v_cvt_pk_bf16_f32 v11, v19, v15
	v_lshl_add_u64 v[14:15], s[8:9], 0, v[138:139]
	v_lshl_add_u64 v[14:15], v[14:15], 0, v[210:211]
	global_store_dwordx4 v[14:15], v[10:13], off sc1
	s_nop 1
	v_add_f32_e32 v10, 1.0, v16
	v_rcp_f32_e32 v10, v10
	v_add_f32_e32 v11, 1.0, v17
	v_rcp_f32_e32 v11, v11
	v_lshlrev_b32_e32 v12, 16, v66
	v_fmac_f32_e32 v12, v6, v10
	v_and_b32_e32 v6, 0xffff0000, v66
	v_fmac_f32_e32 v6, v7, v11
	v_lshlrev_b32_e32 v7, 16, v75
	v_add_f32_e32 v7, v80, v7
	v_and_b32_e32 v10, 0xffff0000, v75
	v_mul_f32_e32 v7, 0xbfb8aa3b, v7
	v_add_f32_e32 v10, v81, v10
	v_exp_f32_e32 v7, v7
	v_mul_f32_e32 v10, 0xbfb8aa3b, v10
	v_exp_f32_e32 v10, v10
	v_lshlrev_b32_e32 v13, 16, v76
	v_add_f32_e32 v7, 1.0, v7
	v_rcp_f32_e32 v7, v7
	v_add_f32_e32 v10, 1.0, v10
	v_rcp_f32_e32 v10, v10
	v_add_f32_e32 v13, v70, v13
	v_mul_f32_e32 v13, 0xbfb8aa3b, v13
	v_lshlrev_b32_e32 v11, 16, v67
	v_exp_f32_e32 v13, v13
	v_fmac_f32_e32 v11, v8, v7
	v_and_b32_e32 v7, 0xffff0000, v67
	v_fmac_f32_e32 v7, v9, v10
	v_and_b32_e32 v9, 0xffff0000, v76
	v_add_f32_e32 v9, v71, v9
	v_add_f32_e32 v8, 1.0, v13
	v_mul_f32_e32 v9, 0xbfb8aa3b, v9
	v_rcp_f32_e32 v8, v8
	v_exp_f32_e32 v9, v9
	v_lshlrev_b32_e32 v10, 16, v68
	v_and_b32_e32 v13, 0xffff0000, v77
	v_fmac_f32_e32 v10, v2, v8
	v_add_f32_e32 v2, 1.0, v9
	v_lshlrev_b32_e32 v9, 16, v77
	v_add_f32_e32 v9, v72, v9
	v_add_f32_e32 v13, v73, v13
	v_mul_f32_e32 v9, 0xbfb8aa3b, v9
	v_mul_f32_e32 v13, 0xbfb8aa3b, v13
	v_rcp_f32_e32 v2, v2
	v_exp_f32_e32 v9, v9
	v_exp_f32_e32 v13, v13
	v_and_b32_e32 v8, 0xffff0000, v68
	v_fmac_f32_e32 v8, v3, v2
	v_add_f32_e32 v2, 1.0, v9
	v_add_f32_e32 v3, 1.0, v13
	v_rcp_f32_e32 v2, v2
	v_rcp_f32_e32 v3, v3
	v_lshlrev_b32_e32 v9, 16, v69
	v_and_b32_e32 v13, 0xffff0000, v69
	v_fmac_f32_e32 v9, v4, v2
	v_fmac_f32_e32 v13, v5, v3
	v_cvt_pk_bf16_f32 v2, v12, v6
	v_cvt_pk_bf16_f32 v3, v11, v7
	v_cvt_pk_bf16_f32 v4, v10, v8
	v_cvt_pk_bf16_f32 v5, v9, v13
	global_store_dwordx4 v[14:15], v[2:5], off offset:256 sc1
	s_cbranch_vccnz .LBB0_1004
	s_andn2_b64 vcc, exec, s[6:7]
	s_cbranch_vccnz .LBB0_1003
	s_barrier
	s_branch .LBB0_1003
